# P0 stores (H, weight transposes, rope tables) write-through (sc1) so SEAM0's L2 write-back has little to flush
# baseline (speedup 1.0000x reference)
; #define LAS __attribute__((address_space(3)))
; __device__ __forceinline__ unsigned pk_bf16(float lo, float hi) { typedef __bf16 b2 __attribute__((ext_vector_type(2))); f32x2 v = {lo, hi}; b2 b = __builtin_convertvector(v, b2); return __builtin_bit_cast(unsigned, b); }
; template <bool MAP> __device__ __forceinline__ void p0_transpose_item(const float* W, int K, int N, u16* WT, LAS float* scr, int item, int lane) {
;     ...
;     for (int j = 0; j < 4; ++j) { const int n = (lane >> 3) + 8 * j; const LAS float* s = scr + (8 * c) * 33 + n;
;         u32x4 o; o.x = pk_bf16(s[0 * 33], s[1 * 33]); o.y = pk_bf16(s[2 * 33], s[3 * 33]); o.z = pk_bf16(s[4 * 33], s[5 * 33]); o.w = pk_bf16(s[6 * 33], s[7 * 33]);
;         const int r = MAP ? wt_row_of_col(n0 + n) : (n0 + n);
;         *(u32x4*)(WT + (size_t)r * K + k0 + 8 * c) = o; }
.LBB0_22:
	s_or_b64 exec, exec, s[10:11]
	v_ashrrev_i32_e32 v23, 31, v22
	s_waitcnt lgkmcnt(3)
	v_cvt_pk_bf16_f32 v14, v14, v15
	s_waitcnt lgkmcnt(2)
	v_cvt_pk_bf16_f32 v15, v16, v17
	s_waitcnt lgkmcnt(1)
	v_cvt_pk_bf16_f32 v16, v18, v19
	v_lshlrev_b64 v[18:19], 11, v[22:23]
	s_waitcnt lgkmcnt(0)
	v_cvt_pk_bf16_f32 v17, v20, v21
	v_lshl_add_u64 v[12:13], v[12:13], 0, v[18:19]
	global_store_dwordx4 v[12:13], v[14:17], off sc1
	s_waitcnt lgkmcnt(0)

; #define LAS __attribute__((address_space(3)))
; __device__ __forceinline__ unsigned pk_bf16(float lo, float hi) { typedef __bf16 b2 __attribute__((ext_vector_type(2))); f32x2 v = {lo, hi}; b2 b = __builtin_convertvector(v, b2); return __builtin_bit_cast(unsigned, b); }
; template <bool MAP> __device__ __forceinline__ void p0_transpose_item(const float* W, int K, int N, u16* WT, LAS float* scr, int item, int lane) {
;     const int nblk = N / 32, kb = item / nblk, nb = item % nblk, k0 = 64 * kb, n0 = 32 * nb;
;     float tv[32];
; #pragma unroll
;     for (int i = 0; i < 32; ++i) tv[i] = W[(size_t)(k0 + 2 * i + (lane >> 5)) * N + n0 + (lane & 31)];
; #pragma unroll
;     for (int i = 0; i < 32; ++i) scr[(2 * i + (lane >> 5)) * 33 + (lane & 31)] = tv[i];
;     asm volatile("s_waitcnt lgkmcnt(0)" ::: "memory");
;     const int c = lane & 7;
; #pragma unroll
;     for (int j = 0; j < 4; ++j) { const int n = (lane >> 3) + 8 * j; const LAS float* s = scr + (8 * c) * 33 + n;
;         u32x4 o; o.x = pk_bf16(s[0 * 33], s[1 * 33]); o.y = pk_bf16(s[2 * 33], s[3 * 33]); o.z = pk_bf16(s[4 * 33], s[5 * 33]); o.w = pk_bf16(s[6 * 33], s[7 * 33]);
; __device__ __forceinline__ void p0_prologue(const Ptrs& P, LAS unsigned char* lds, int vcu, int G) {
;     ...
;         p0_transpose_item<false>(P.wo, 1024, 1024, (u16*)(P.ws + WS_WO), scr, r, lane);
.LBB0_24:
	s_cmpk_gt_i32 s28, 0x15ff
	s_mov_b64 s[8:9], -1
	s_cbranch_scc0 .LBB0_34
	s_cmpk_gt_u32 s28, 0x17ff
	s_cbranch_scc0 .LBB0_31
	s_cmpk_gt_u32 s28, 0x18ff
	s_cbranch_scc0 .LBB0_28
	s_add_i32 s8, s18, 0xfffce000
	s_and_b32 s8, s8, 0x3e0
	s_and_b32 s9, s21, 0xf0000
	s_or_b32 s9, s9, s8
	v_or_b32_e32 v0, s9, v26
	v_or_b32_e32 v14, s9, v29
	v_or_b32_e32 v15, s9, v30
	v_or_b32_e32 v16, s9, v31
	v_or_b32_e32 v17, s9, v32
	v_or_b32_e32 v18, s9, v33
	v_lshlrev_b32_e32 v0, 2, v0
	v_or_b32_e32 v12, s9, v27
	v_or_b32_e32 v13, s9, v28
	v_lshlrev_b32_e32 v14, 2, v14
	v_lshlrev_b32_e32 v15, 2, v15
	v_lshlrev_b32_e32 v16, 2, v16
	v_lshlrev_b32_e32 v17, 2, v17
	v_lshlrev_b32_e32 v18, 2, v18
	v_lshlrev_b32_e32 v12, 2, v12
	v_lshlrev_b32_e32 v13, 2, v13
	global_load_dword v19, v0, s[72:73]
	global_load_dword v20, v12, s[72:73]
	global_load_dword v21, v13, s[72:73]
	s_nop 0
	global_load_dword v14, v14, s[72:73]
	s_nop 0
	global_load_dword v15, v15, s[72:73]
	s_nop 0
	global_load_dword v16, v16, s[72:73]
	s_nop 0
	global_load_dword v17, v17, s[72:73]
	s_nop 0
	global_load_dword v18, v18, s[72:73]
	v_or_b32_e32 v0, s9, v34
	v_or_b32_e32 v22, s9, v37
	v_or_b32_e32 v23, s9, v38
	v_or_b32_e32 v71, s9, v39
	v_or_b32_e32 v72, s9, v40
	v_or_b32_e32 v73, s9, v41
	v_lshlrev_b32_e32 v0, 2, v0
	v_or_b32_e32 v12, s9, v35
	v_or_b32_e32 v13, s9, v36
	v_lshlrev_b32_e32 v22, 2, v22
	v_lshlrev_b32_e32 v23, 2, v23
	v_lshlrev_b32_e32 v71, 2, v71
	v_lshlrev_b32_e32 v72, 2, v72
	v_lshlrev_b32_e32 v73, 2, v73
	v_lshlrev_b32_e32 v12, 2, v12
	v_lshlrev_b32_e32 v13, 2, v13
	global_load_dword v74, v0, s[72:73]
	global_load_dword v75, v12, s[72:73]
	global_load_dword v76, v13, s[72:73]
	s_nop 0
	global_load_dword v22, v22, s[72:73]
	s_nop 0
	global_load_dword v23, v23, s[72:73]
	s_nop 0
	global_load_dword v71, v71, s[72:73]
	s_nop 0
	global_load_dword v72, v72, s[72:73]
	s_nop 0
	global_load_dword v73, v73, s[72:73]
	v_or_b32_e32 v0, s9, v42
	v_or_b32_e32 v77, s9, v45
	v_or_b32_e32 v78, s9, v46
	v_or_b32_e32 v79, s9, v47
	v_or_b32_e32 v80, s9, v48
	v_or_b32_e32 v81, s9, v49
	v_lshlrev_b32_e32 v0, 2, v0
	v_or_b32_e32 v12, s9, v43
	v_or_b32_e32 v13, s9, v44
	v_lshlrev_b32_e32 v77, 2, v77
	v_lshlrev_b32_e32 v78, 2, v78
	v_lshlrev_b32_e32 v79, 2, v79
	v_lshlrev_b32_e32 v80, 2, v80
	v_lshlrev_b32_e32 v81, 2, v81
	v_lshlrev_b32_e32 v12, 2, v12
	v_lshlrev_b32_e32 v13, 2, v13
	global_load_dword v82, v0, s[72:73]
	global_load_dword v83, v12, s[72:73]
	global_load_dword v84, v13, s[72:73]
	s_nop 0
	global_load_dword v77, v77, s[72:73]
	s_nop 0
	global_load_dword v78, v78, s[72:73]
	s_nop 0
	global_load_dword v79, v79, s[72:73]
	s_nop 0
	global_load_dword v80, v80, s[72:73]
	s_nop 0
	global_load_dword v81, v81, s[72:73]
	v_or_b32_e32 v0, s9, v50
	v_lshlrev_b32_e32 v85, 2, v0
	v_or_b32_e32 v0, s9, v51
	v_lshlrev_b32_e32 v86, 2, v0
	v_or_b32_e32 v0, s9, v52
	v_lshlrev_b32_e32 v87, 2, v0
	v_or_b32_e32 v0, s9, v53
	v_lshlrev_b32_e32 v88, 2, v0
	v_or_b32_e32 v0, s9, v54
	s_and_b32 s6, s20, 0x3e0
	v_lshlrev_b32_e32 v89, 2, v0
	v_or_b32_e32 v0, s9, v55
	v_lshlrev_b32_e32 v90, 2, v0
	v_or_b32_e32 v0, s9, v56
	s_add_i32 s6, s6, s21
	v_lshlrev_b32_e32 v91, 2, v0
	v_add_u32_e32 v0, s6, v26
	v_or_b32_e32 v0, 0xf800, v0
	v_lshl_add_u64 v[12:13], v[0:1], 2, s[72:73]
	global_load_dword v0, v85, s[72:73]
	s_nop 0
	global_load_dword v85, v86, s[72:73]
	s_nop 0
	global_load_dword v86, v87, s[72:73]
	s_nop 0
	global_load_dword v87, v88, s[72:73]
	s_nop 0
	global_load_dword v88, v89, s[72:73]
	s_nop 0
	global_load_dword v89, v90, s[72:73]
	s_nop 0
	global_load_dword v90, v91, s[72:73]
	s_nop 0
	global_load_dword v12, v[12:13], off
	s_and_b32 s6, s23, 0x3c0
	s_lshl_b32 s6, s6, 1
	s_waitcnt vmcnt(30)
	ds_write2_b32 v62, v19, v20 offset1:66
	s_waitcnt vmcnt(28)
	ds_write2_b32 v62, v21, v14 offset0:132 offset1:198
	s_waitcnt vmcnt(26)
	ds_write2_b32 v64, v15, v16 offset0:8 offset1:74
	s_waitcnt vmcnt(24)
	ds_write2_b32 v64, v17, v18 offset0:140 offset1:206
	s_waitcnt vmcnt(22)
	ds_write2_b32 v65, v74, v75 offset0:16 offset1:82
	s_waitcnt vmcnt(20)
	ds_write2_b32 v65, v76, v22 offset0:148 offset1:214
	s_waitcnt vmcnt(18)
	ds_write2_b32 v66, v23, v71 offset0:24 offset1:90
	s_waitcnt vmcnt(16)
	ds_write2_b32 v66, v72, v73 offset0:156 offset1:222
	s_waitcnt vmcnt(14)
	ds_write2_b32 v67, v82, v83 offset0:32 offset1:98
	s_waitcnt vmcnt(12)
	ds_write2_b32 v67, v84, v77 offset0:164 offset1:230
	s_waitcnt vmcnt(10)
	ds_write2_b32 v68, v78, v79 offset0:40 offset1:106
	s_waitcnt vmcnt(8)
	ds_write2_b32 v68, v80, v81 offset0:172 offset1:238
	s_waitcnt vmcnt(6)
	ds_write2_b32 v69, v0, v85 offset0:48 offset1:114
	s_waitcnt vmcnt(4)
	ds_write2_b32 v69, v86, v87 offset0:180 offset1:246
	s_waitcnt vmcnt(2)
	ds_write2_b32 v70, v88, v89 offset0:56 offset1:122
	s_waitcnt vmcnt(0)
	ds_write2_b32 v70, v90, v12 offset0:188 offset1:254
	s_waitcnt lgkmcnt(0)
	ds_read2_b32 v[16:17], v63 offset0:33 offset1:41
	ds_read2_b32 v[18:19], v63 offset1:8
	ds_read2_b32 v[20:21], v63 offset0:66 offset1:74
	ds_read2_b32 v[22:23], v63 offset0:99 offset1:107
	ds_read2_b32 v[72:73], v63 offset0:132 offset1:140
	ds_read2_b32 v[74:75], v63 offset0:165 offset1:173
	ds_read2_b32 v[76:77], v63 offset0:198 offset1:206
	ds_read2_b32 v[78:79], v63 offset0:231 offset1:239
	v_or_b32_e32 v0, s8, v58
	v_lshl_add_u64 v[80:81], v[6:7], 0, s[6:7]
	v_lshlrev_b32_e32 v0, 11, v0
	s_waitcnt lgkmcnt(6)
	v_cvt_pk_bf16_f32 v12, v18, v16
	s_waitcnt lgkmcnt(4)
	v_cvt_pk_bf16_f32 v13, v20, v22
	s_waitcnt lgkmcnt(2)
	v_cvt_pk_bf16_f32 v14, v72, v74
	s_waitcnt lgkmcnt(0)
; #define LAS __attribute__((address_space(3)))
; __device__ __forceinline__ unsigned pk_bf16(float lo, float hi) { typedef __bf16 b2 __attribute__((ext_vector_type(2))); f32x2 v = {lo, hi}; b2 b = __builtin_convertvector(v, b2); return __builtin_bit_cast(unsigned, b); }
; template <bool MAP> __device__ __forceinline__ void p0_transpose_item(const float* W, int K, int N, u16* WT, LAS float* scr, int item, int lane) {
;     ...
;     for (int j = 0; j < 4; ++j) { const int n = (lane >> 3) + 8 * j; const LAS float* s = scr + (8 * c) * 33 + n;
;         u32x4 o; o.x = pk_bf16(s[0 * 33], s[1 * 33]); o.y = pk_bf16(s[2 * 33], s[3 * 33]); o.z = pk_bf16(s[4 * 33], s[5 * 33]); o.w = pk_bf16(s[6 * 33], s[7 * 33]);
;         const int r = MAP ? wt_row_of_col(n0 + n) : (n0 + n);
;         *(u32x4*)(WT + (size_t)r * K + k0 + 8 * c) = o; }
;     asm volatile("s_waitcnt lgkmcnt(0)" ::: "memory");
	v_cvt_pk_bf16_f32 v15, v76, v78
	v_lshl_add_u64 v[82:83], v[80:81], 0, v[0:1]
	global_store_dwordx4 v[82:83], v[12:15], off sc1
	v_or_b32_e32 v0, s8, v59
	v_lshlrev_b32_e32 v0, 11, v0
	v_cvt_pk_bf16_f32 v12, v19, v17
	v_cvt_pk_bf16_f32 v13, v21, v23
	v_cvt_pk_bf16_f32 v14, v73, v75
	v_cvt_pk_bf16_f32 v15, v77, v79
	ds_read2_b32 v[18:19], v63 offset0:49 offset1:57
	ds_read2_b32 v[20:21], v63 offset0:16 offset1:24
	ds_read2_b32 v[22:23], v63 offset0:82 offset1:90
	ds_read2_b32 v[72:73], v63 offset0:115 offset1:123
	ds_read2_b32 v[74:75], v63 offset0:148 offset1:156
	ds_read2_b32 v[76:77], v63 offset0:181 offset1:189
	ds_read2_b32 v[78:79], v63 offset0:214 offset1:222
	ds_read2_b32 v[82:83], v63 offset0:247 offset1:255
	v_lshl_add_u64 v[16:17], v[80:81], 0, v[0:1]
	v_or_b32_e32 v0, s8, v60
	v_lshlrev_b32_e32 v0, 11, v0
	global_store_dwordx4 v[16:17], v[12:15], off sc1
	v_lshl_add_u64 v[16:17], v[80:81], 0, v[0:1]
	v_or_b32_e32 v0, s8, v61
	s_waitcnt lgkmcnt(6)
	v_cvt_pk_bf16_f32 v12, v20, v18
	s_waitcnt lgkmcnt(4)
	v_cvt_pk_bf16_f32 v13, v22, v72
	s_waitcnt lgkmcnt(2)
	v_cvt_pk_bf16_f32 v14, v74, v76
	s_waitcnt lgkmcnt(0)
	v_cvt_pk_bf16_f32 v15, v78, v82
	v_lshlrev_b32_e32 v0, 11, v0
	global_store_dwordx4 v[16:17], v[12:15], off sc1
	v_lshl_add_u64 v[16:17], v[80:81], 0, v[0:1]
	s_mov_b64 s[8:9], 0
	v_cvt_pk_bf16_f32 v12, v21, v19
	v_cvt_pk_bf16_f32 v13, v23, v73
	v_cvt_pk_bf16_f32 v14, v75, v77
	v_cvt_pk_bf16_f32 v15, v79, v83
	global_store_dwordx4 v[16:17], v[12:15], off sc1
	s_waitcnt lgkmcnt(0)
; #define LAS __attribute__((address_space(3)))
; __device__ __forceinline__ unsigned pk_bf16(float lo, float hi) { typedef __bf16 b2 __attribute__((ext_vector_type(2))); f32x2 v = {lo, hi}; b2 b = __builtin_convertvector(v, b2); return __builtin_bit_cast(unsigned, b); }
; template <bool MAP> __device__ __forceinline__ void p0_transpose_item(const float* W, int K, int N, u16* WT, LAS float* scr, int item, int lane) {
;     const int nblk = N / 32, kb = item / nblk, nb = item % nblk, k0 = 64 * kb, n0 = 32 * nb;
;     float tv[32];
; #pragma unroll
;     for (int i = 0; i < 32; ++i) tv[i] = W[(size_t)(k0 + 2 * i + (lane >> 5)) * N + n0 + (lane & 31)];
; #pragma unroll
;     for (int i = 0; i < 32; ++i) scr[(2 * i + (lane >> 5)) * 33 + (lane & 31)] = tv[i];
;     asm volatile("s_waitcnt lgkmcnt(0)" ::: "memory");
;     const int c = lane & 7;
; #pragma unroll
;     for (int j = 0; j < 4; ++j) { const int n = (lane >> 3) + 8 * j; const LAS float* s = scr + (8 * c) * 33 + n;
;         u32x4 o; o.x = pk_bf16(s[0 * 33], s[1 * 33]); o.y = pk_bf16(s[2 * 33], s[3 * 33]); o.z = pk_bf16(s[4 * 33], s[5 * 33]); o.w = pk_bf16(s[6 * 33], s[7 * 33]);
;         const int r = MAP ? wt_row_of_col(n0 + n) : (n0 + n);
;         *(u32x4*)(WT + (size_t)r * K + k0 + 8 * c) = o; }
;     asm volatile("s_waitcnt lgkmcnt(0)" ::: "memory");
; __device__ __forceinline__ void p0_prologue(const Ptrs& P, LAS unsigned char* lds, int vcu, int G) {
;     ...
;         if (r < I_B) { p0_transpose_item<false>(P.wb, 512, 1024, (u16*)(P.ws + WS_WB), scr, r, lane); continue; } r -= I_B;
.LBB0_28:
	s_andn2_b64 vcc, exec, s[8:9]
	s_cbranch_vccnz .LBB0_30
	s_add_i32 s8, s18, 0xfffd0000
	s_add_i32 s9, s21, 0xc80000
	s_and_b32 s8, s8, 0x3e0
	s_and_b32 s9, s9, 0xf0000
	s_or_b32 s9, s8, s9
	v_or_b32_e32 v0, s9, v26
	v_or_b32_e32 v14, s9, v29
	v_or_b32_e32 v15, s9, v30
	v_or_b32_e32 v16, s9, v31
	v_or_b32_e32 v17, s9, v32
	v_or_b32_e32 v18, s9, v33
	v_lshlrev_b32_e32 v0, 2, v0
	v_or_b32_e32 v12, s9, v27
	v_or_b32_e32 v13, s9, v28
	v_lshlrev_b32_e32 v14, 2, v14
	v_lshlrev_b32_e32 v15, 2, v15
	v_lshlrev_b32_e32 v16, 2, v16
	v_lshlrev_b32_e32 v17, 2, v17
	v_lshlrev_b32_e32 v18, 2, v18
	v_lshlrev_b32_e32 v12, 2, v12
	v_lshlrev_b32_e32 v13, 2, v13
	global_load_dword v19, v0, s[70:71]
	global_load_dword v20, v12, s[70:71]
	global_load_dword v21, v13, s[70:71]
	s_nop 0
	global_load_dword v14, v14, s[70:71]
	s_nop 0
	global_load_dword v15, v15, s[70:71]
	s_nop 0
	global_load_dword v16, v16, s[70:71]
	s_nop 0
	global_load_dword v17, v17, s[70:71]
	s_nop 0
	global_load_dword v18, v18, s[70:71]
	v_or_b32_e32 v0, s9, v34
	v_or_b32_e32 v22, s9, v37
	v_or_b32_e32 v23, s9, v38
	v_or_b32_e32 v71, s9, v39
	v_or_b32_e32 v72, s9, v40
	v_or_b32_e32 v73, s9, v41
	v_lshlrev_b32_e32 v0, 2, v0
	v_or_b32_e32 v12, s9, v35
	v_or_b32_e32 v13, s9, v36
	v_lshlrev_b32_e32 v22, 2, v22
	v_lshlrev_b32_e32 v23, 2, v23
	v_lshlrev_b32_e32 v71, 2, v71
	v_lshlrev_b32_e32 v72, 2, v72
	v_lshlrev_b32_e32 v73, 2, v73
	v_lshlrev_b32_e32 v12, 2, v12
	v_lshlrev_b32_e32 v13, 2, v13
	global_load_dword v74, v0, s[70:71]
	global_load_dword v75, v12, s[70:71]
	global_load_dword v76, v13, s[70:71]
	s_nop 0
	global_load_dword v22, v22, s[70:71]
	s_nop 0
	global_load_dword v23, v23, s[70:71]
	s_nop 0
	global_load_dword v71, v71, s[70:71]
	s_nop 0
	global_load_dword v72, v72, s[70:71]
	s_nop 0
	global_load_dword v73, v73, s[70:71]
	v_or_b32_e32 v0, s9, v42
	v_or_b32_e32 v77, s9, v45
	v_or_b32_e32 v78, s9, v46
	v_or_b32_e32 v79, s9, v47
	v_or_b32_e32 v80, s9, v48
	v_or_b32_e32 v81, s9, v49
	v_lshlrev_b32_e32 v0, 2, v0
	v_or_b32_e32 v12, s9, v43
	v_or_b32_e32 v13, s9, v44
	v_lshlrev_b32_e32 v77, 2, v77
	v_lshlrev_b32_e32 v78, 2, v78
	v_lshlrev_b32_e32 v79, 2, v79
	v_lshlrev_b32_e32 v80, 2, v80
	v_lshlrev_b32_e32 v81, 2, v81
	v_lshlrev_b32_e32 v12, 2, v12
	v_lshlrev_b32_e32 v13, 2, v13
	global_load_dword v82, v0, s[70:71]
	global_load_dword v83, v12, s[70:71]
	global_load_dword v84, v13, s[70:71]
	s_nop 0
	global_load_dword v77, v77, s[70:71]
	s_nop 0
	global_load_dword v78, v78, s[70:71]
	s_nop 0
	global_load_dword v79, v79, s[70:71]
	s_nop 0
	global_load_dword v80, v80, s[70:71]
	s_nop 0
	global_load_dword v81, v81, s[70:71]
	v_or_b32_e32 v0, s9, v50
	v_lshlrev_b32_e32 v85, 2, v0
	v_or_b32_e32 v0, s9, v51
	v_lshlrev_b32_e32 v86, 2, v0
	v_or_b32_e32 v0, s9, v52
	v_lshlrev_b32_e32 v87, 2, v0
	v_or_b32_e32 v0, s9, v53
	v_lshlrev_b32_e32 v88, 2, v0
	v_or_b32_e32 v0, s9, v54
	s_and_b32 s6, s25, 0x3e0
	v_lshlrev_b32_e32 v89, 2, v0
	v_or_b32_e32 v0, s9, v55
	v_lshlrev_b32_e32 v90, 2, v0
	v_or_b32_e32 v0, s9, v56
	s_add_i32 s6, s6, s21
	v_lshlrev_b32_e32 v91, 2, v0
	v_add_u32_e32 v0, s6, v26
	v_add_u32_e32 v0, 0x80000, v0
	v_or_b32_e32 v0, 0xf800, v0
	v_lshl_add_u64 v[12:13], v[0:1], 2, s[70:71]
	global_load_dword v0, v85, s[70:71]
	s_nop 0
	global_load_dword v85, v86, s[70:71]
	s_nop 0
	global_load_dword v86, v87, s[70:71]
	s_nop 0
	global_load_dword v87, v88, s[70:71]
	s_nop 0
	global_load_dword v88, v89, s[70:71]
	s_nop 0
	global_load_dword v89, v90, s[70:71]
	s_nop 0
	global_load_dword v90, v91, s[70:71]
	s_nop 0
	global_load_dword v12, v[12:13], off
	s_add_i32 s6, s23, 0x200
	s_and_b32 s6, s6, 0x3c0
	s_lshl_b32 s6, s6, 1
	s_waitcnt vmcnt(30)
	ds_write2_b32 v62, v19, v20 offset1:66
	s_waitcnt vmcnt(28)
	ds_write2_b32 v62, v21, v14 offset0:132 offset1:198
	s_waitcnt vmcnt(26)
	ds_write2_b32 v64, v15, v16 offset0:8 offset1:74
	s_waitcnt vmcnt(24)
	ds_write2_b32 v64, v17, v18 offset0:140 offset1:206
	s_waitcnt vmcnt(22)
	ds_write2_b32 v65, v74, v75 offset0:16 offset1:82
	s_waitcnt vmcnt(20)
	ds_write2_b32 v65, v76, v22 offset0:148 offset1:214
	s_waitcnt vmcnt(18)
	ds_write2_b32 v66, v23, v71 offset0:24 offset1:90
	s_waitcnt vmcnt(16)
	ds_write2_b32 v66, v72, v73 offset0:156 offset1:222
	s_waitcnt vmcnt(14)
	ds_write2_b32 v67, v82, v83 offset0:32 offset1:98
	s_waitcnt vmcnt(12)
	ds_write2_b32 v67, v84, v77 offset0:164 offset1:230
	s_waitcnt vmcnt(10)
	ds_write2_b32 v68, v78, v79 offset0:40 offset1:106
	s_waitcnt vmcnt(8)
	ds_write2_b32 v68, v80, v81 offset0:172 offset1:238
	s_waitcnt vmcnt(6)
	ds_write2_b32 v69, v0, v85 offset0:48 offset1:114
	s_waitcnt vmcnt(4)
	ds_write2_b32 v69, v86, v87 offset0:180 offset1:246
	s_waitcnt vmcnt(2)
	ds_write2_b32 v70, v88, v89 offset0:56 offset1:122
	s_waitcnt vmcnt(0)
	ds_write2_b32 v70, v90, v12 offset0:188 offset1:254
	s_waitcnt lgkmcnt(0)
	ds_read2_b32 v[16:17], v63 offset0:33 offset1:41
	ds_read2_b32 v[18:19], v63 offset1:8
	ds_read2_b32 v[20:21], v63 offset0:66 offset1:74
	ds_read2_b32 v[22:23], v63 offset0:99 offset1:107
	ds_read2_b32 v[72:73], v63 offset0:132 offset1:140
	ds_read2_b32 v[74:75], v63 offset0:165 offset1:173
	ds_read2_b32 v[76:77], v63 offset0:198 offset1:206
	ds_read2_b32 v[78:79], v63 offset0:231 offset1:239
	v_or_b32_e32 v0, s8, v58
	v_lshl_add_u64 v[80:81], v[8:9], 0, s[6:7]
	v_lshlrev_b32_e32 v0, 10, v0
	s_waitcnt lgkmcnt(6)
	v_cvt_pk_bf16_f32 v12, v18, v16
	s_waitcnt lgkmcnt(4)
	v_cvt_pk_bf16_f32 v13, v20, v22
	s_waitcnt lgkmcnt(2)
	v_cvt_pk_bf16_f32 v14, v72, v74
	s_waitcnt lgkmcnt(0)
	v_cvt_pk_bf16_f32 v15, v76, v78
	v_lshl_add_u64 v[82:83], v[80:81], 0, v[0:1]
	global_store_dwordx4 v[82:83], v[12:15], off sc1
	v_or_b32_e32 v0, s8, v59
	v_lshlrev_b32_e32 v0, 10, v0
	v_cvt_pk_bf16_f32 v12, v19, v17
	v_cvt_pk_bf16_f32 v13, v21, v23
	v_cvt_pk_bf16_f32 v14, v73, v75
	v_cvt_pk_bf16_f32 v15, v77, v79
	ds_read2_b32 v[18:19], v63 offset0:49 offset1:57
	ds_read2_b32 v[20:21], v63 offset0:16 offset1:24
	ds_read2_b32 v[22:23], v63 offset0:82 offset1:90
	ds_read2_b32 v[72:73], v63 offset0:115 offset1:123
	ds_read2_b32 v[74:75], v63 offset0:148 offset1:156
	ds_read2_b32 v[76:77], v63 offset0:181 offset1:189
	ds_read2_b32 v[78:79], v63 offset0:214 offset1:222
	ds_read2_b32 v[82:83], v63 offset0:247 offset1:255
	v_lshl_add_u64 v[16:17], v[80:81], 0, v[0:1]
	v_or_b32_e32 v0, s8, v60
	v_lshlrev_b32_e32 v0, 10, v0
	global_store_dwordx4 v[16:17], v[12:15], off sc1
	v_lshl_add_u64 v[16:17], v[80:81], 0, v[0:1]
	v_or_b32_e32 v0, s8, v61
	s_waitcnt lgkmcnt(6)
	v_cvt_pk_bf16_f32 v12, v20, v18
	s_waitcnt lgkmcnt(4)
	v_cvt_pk_bf16_f32 v13, v22, v72
	s_waitcnt lgkmcnt(2)
	v_cvt_pk_bf16_f32 v14, v74, v76
	s_waitcnt lgkmcnt(0)
	v_cvt_pk_bf16_f32 v15, v78, v82
	v_lshlrev_b32_e32 v0, 10, v0
	global_store_dwordx4 v[16:17], v[12:15], off sc1
	v_lshl_add_u64 v[16:17], v[80:81], 0, v[0:1]
	s_nop 0
	v_cvt_pk_bf16_f32 v12, v21, v19
	v_cvt_pk_bf16_f32 v13, v23, v73
	v_cvt_pk_bf16_f32 v14, v75, v77
	v_cvt_pk_bf16_f32 v15, v79, v83
	global_store_dwordx4 v[16:17], v[12:15], off sc1
	s_waitcnt lgkmcnt(0)

; #define LAS __attribute__((address_space(3)))
; __device__ __forceinline__ unsigned pk_bf16(float lo, float hi) { typedef __bf16 b2 __attribute__((ext_vector_type(2))); f32x2 v = {lo, hi}; b2 b = __builtin_convertvector(v, b2); return __builtin_bit_cast(unsigned, b); }
; template <bool MAP> __device__ __forceinline__ void p0_transpose_item(const float* W, int K, int N, u16* WT, LAS float* scr, int item, int lane) {
;     const int nblk = N / 32, kb = item / nblk, nb = item % nblk, k0 = 64 * kb, n0 = 32 * nb;
;     float tv[32];
; #pragma unroll
;     for (int i = 0; i < 32; ++i) tv[i] = W[(size_t)(k0 + 2 * i + (lane >> 5)) * N + n0 + (lane & 31)];
; #pragma unroll
;     for (int i = 0; i < 32; ++i) scr[(2 * i + (lane >> 5)) * 33 + (lane & 31)] = tv[i];
;     asm volatile("s_waitcnt lgkmcnt(0)" ::: "memory");
;     const int c = lane & 7;
; #pragma unroll
;     for (int j = 0; j < 4; ++j) { const int n = (lane >> 3) + 8 * j; const LAS float* s = scr + (8 * c) * 33 + n;
;         u32x4 o; o.x = pk_bf16(s[0 * 33], s[1 * 33]); o.y = pk_bf16(s[2 * 33], s[3 * 33]); o.z = pk_bf16(s[4 * 33], s[5 * 33]); o.w = pk_bf16(s[6 * 33], s[7 * 33]);
;         const int r = MAP ? wt_row_of_col(n0 + n) : (n0 + n);
;         *(u32x4*)(WT + (size_t)r * K + k0 + 8 * c) = o; }
;     asm volatile("s_waitcnt lgkmcnt(0)" ::: "memory");
; __device__ __forceinline__ void p0_prologue(const Ptrs& P, LAS unsigned char* lds, int vcu, int G) {
;     ...
;         if (r < I_A) { p0_transpose_item<false>(P.wa, 1024, 1024, (u16*)(P.ws + WS_WA), scr, r, lane); continue; } r -= I_A;
.LBB0_31:
	s_andn2_b64 vcc, exec, s[8:9]
	s_cbranch_vccnz .LBB0_33
	s_add_i32 s8, s18, 0xfffd4000
	s_add_i32 s9, s21, 0xc80000
	s_and_b32 s8, s8, 0x3e0
	s_and_b32 s9, s9, 0xf0000
	s_or_b32 s9, s8, s9
	v_or_b32_e32 v0, s9, v26
	v_or_b32_e32 v14, s9, v29
	v_or_b32_e32 v15, s9, v30
	v_or_b32_e32 v16, s9, v31
	v_or_b32_e32 v17, s9, v32
	v_or_b32_e32 v18, s9, v33
	v_lshlrev_b32_e32 v0, 2, v0
	v_or_b32_e32 v12, s9, v27
	v_or_b32_e32 v13, s9, v28
	v_lshlrev_b32_e32 v14, 2, v14
	v_lshlrev_b32_e32 v15, 2, v15
	v_lshlrev_b32_e32 v16, 2, v16
	v_lshlrev_b32_e32 v17, 2, v17
	v_lshlrev_b32_e32 v18, 2, v18
	v_lshlrev_b32_e32 v12, 2, v12
	v_lshlrev_b32_e32 v13, 2, v13
	global_load_dword v19, v0, s[68:69]
	global_load_dword v20, v12, s[68:69]
	global_load_dword v21, v13, s[68:69]
	s_nop 0
	global_load_dword v14, v14, s[68:69]
	s_nop 0
	global_load_dword v15, v15, s[68:69]
	s_nop 0
	global_load_dword v16, v16, s[68:69]
	s_nop 0
	global_load_dword v17, v17, s[68:69]
	s_nop 0
	global_load_dword v18, v18, s[68:69]
	v_or_b32_e32 v0, s9, v34
	v_or_b32_e32 v22, s9, v37
	v_or_b32_e32 v23, s9, v38
	v_or_b32_e32 v71, s9, v39
	v_or_b32_e32 v72, s9, v40
	v_or_b32_e32 v73, s9, v41
	v_lshlrev_b32_e32 v0, 2, v0
	v_or_b32_e32 v12, s9, v35
	v_or_b32_e32 v13, s9, v36
	v_lshlrev_b32_e32 v22, 2, v22
	v_lshlrev_b32_e32 v23, 2, v23
	v_lshlrev_b32_e32 v71, 2, v71
	v_lshlrev_b32_e32 v72, 2, v72
	v_lshlrev_b32_e32 v73, 2, v73
	v_lshlrev_b32_e32 v12, 2, v12
	v_lshlrev_b32_e32 v13, 2, v13
	global_load_dword v74, v0, s[68:69]
	global_load_dword v75, v12, s[68:69]
	global_load_dword v76, v13, s[68:69]
	s_nop 0
	global_load_dword v22, v22, s[68:69]
	s_nop 0
	global_load_dword v23, v23, s[68:69]
	s_nop 0
	global_load_dword v71, v71, s[68:69]
	s_nop 0
	global_load_dword v72, v72, s[68:69]
	s_nop 0
	global_load_dword v73, v73, s[68:69]
	v_or_b32_e32 v0, s9, v42
	v_or_b32_e32 v77, s9, v45
	v_or_b32_e32 v78, s9, v46
	v_or_b32_e32 v79, s9, v47
	v_or_b32_e32 v80, s9, v48
	v_or_b32_e32 v81, s9, v49
	v_lshlrev_b32_e32 v0, 2, v0
	v_or_b32_e32 v12, s9, v43
	v_or_b32_e32 v13, s9, v44
	v_lshlrev_b32_e32 v77, 2, v77
	v_lshlrev_b32_e32 v78, 2, v78
	v_lshlrev_b32_e32 v79, 2, v79
	v_lshlrev_b32_e32 v80, 2, v80
	v_lshlrev_b32_e32 v81, 2, v81
	v_lshlrev_b32_e32 v12, 2, v12
	v_lshlrev_b32_e32 v13, 2, v13
	global_load_dword v82, v0, s[68:69]
	global_load_dword v83, v12, s[68:69]
	global_load_dword v84, v13, s[68:69]
	s_nop 0
	global_load_dword v77, v77, s[68:69]
	s_nop 0
	global_load_dword v78, v78, s[68:69]
	s_nop 0
	global_load_dword v79, v79, s[68:69]
	s_nop 0
	global_load_dword v80, v80, s[68:69]
	s_nop 0
	global_load_dword v81, v81, s[68:69]
	v_or_b32_e32 v0, s9, v50
	v_lshlrev_b32_e32 v85, 2, v0
	v_or_b32_e32 v0, s9, v51
	v_lshlrev_b32_e32 v86, 2, v0
	v_or_b32_e32 v0, s9, v52
	v_lshlrev_b32_e32 v87, 2, v0
	v_or_b32_e32 v0, s9, v53
	v_lshlrev_b32_e32 v88, 2, v0
	v_or_b32_e32 v0, s9, v54
	s_and_b32 s6, s26, 0x3e0
	v_lshlrev_b32_e32 v89, 2, v0
	v_or_b32_e32 v0, s9, v55
	v_lshlrev_b32_e32 v90, 2, v0
	v_or_b32_e32 v0, s9, v56
	s_add_i32 s6, s6, s21
	v_lshlrev_b32_e32 v91, 2, v0
	v_add_u32_e32 v0, s6, v26
	v_add_u32_e32 v0, 0x180000, v0
	v_or_b32_e32 v0, 0xf800, v0
	v_lshl_add_u64 v[12:13], v[0:1], 2, s[68:69]
	global_load_dword v0, v85, s[68:69]
	s_nop 0
	global_load_dword v85, v86, s[68:69]
	s_nop 0
	global_load_dword v86, v87, s[68:69]
	s_nop 0
	global_load_dword v87, v88, s[68:69]
	s_nop 0
	global_load_dword v88, v89, s[68:69]
	s_nop 0
	global_load_dword v89, v90, s[68:69]
	s_nop 0
	global_load_dword v90, v91, s[68:69]
	s_nop 0
	global_load_dword v12, v[12:13], off
	s_add_i32 s6, s23, 0x600
	s_and_b32 s6, s6, 0x3c0
	s_lshl_b32 s6, s6, 1
	s_waitcnt vmcnt(30)
	ds_write2_b32 v62, v19, v20 offset1:66
	s_waitcnt vmcnt(28)
	ds_write2_b32 v62, v21, v14 offset0:132 offset1:198
	s_waitcnt vmcnt(26)
	ds_write2_b32 v64, v15, v16 offset0:8 offset1:74
	s_waitcnt vmcnt(24)
	ds_write2_b32 v64, v17, v18 offset0:140 offset1:206
	s_waitcnt vmcnt(22)
	ds_write2_b32 v65, v74, v75 offset0:16 offset1:82
	s_waitcnt vmcnt(20)
	ds_write2_b32 v65, v76, v22 offset0:148 offset1:214
	s_waitcnt vmcnt(18)
	ds_write2_b32 v66, v23, v71 offset0:24 offset1:90
	s_waitcnt vmcnt(16)
	ds_write2_b32 v66, v72, v73 offset0:156 offset1:222
	s_waitcnt vmcnt(14)
	ds_write2_b32 v67, v82, v83 offset0:32 offset1:98
	s_waitcnt vmcnt(12)
	ds_write2_b32 v67, v84, v77 offset0:164 offset1:230
	s_waitcnt vmcnt(10)
	ds_write2_b32 v68, v78, v79 offset0:40 offset1:106
	s_waitcnt vmcnt(8)
	ds_write2_b32 v68, v80, v81 offset0:172 offset1:238
	s_waitcnt vmcnt(6)
	ds_write2_b32 v69, v0, v85 offset0:48 offset1:114
	s_waitcnt vmcnt(4)
	ds_write2_b32 v69, v86, v87 offset0:180 offset1:246
	s_waitcnt vmcnt(2)
	ds_write2_b32 v70, v88, v89 offset0:56 offset1:122
	s_waitcnt vmcnt(0)
	ds_write2_b32 v70, v90, v12 offset0:188 offset1:254
	s_waitcnt lgkmcnt(0)
	ds_read2_b32 v[16:17], v63 offset0:33 offset1:41
	ds_read2_b32 v[18:19], v63 offset1:8
	ds_read2_b32 v[20:21], v63 offset0:66 offset1:74
	ds_read2_b32 v[22:23], v63 offset0:99 offset1:107
	ds_read2_b32 v[72:73], v63 offset0:132 offset1:140
	ds_read2_b32 v[74:75], v63 offset0:165 offset1:173
	ds_read2_b32 v[76:77], v63 offset0:198 offset1:206
	ds_read2_b32 v[78:79], v63 offset0:231 offset1:239
	v_or_b32_e32 v0, s8, v58
	v_lshl_add_u64 v[80:81], v[10:11], 0, s[6:7]
	v_lshlrev_b32_e32 v0, 11, v0
	s_waitcnt lgkmcnt(6)
	v_cvt_pk_bf16_f32 v12, v18, v16
	s_waitcnt lgkmcnt(4)
	v_cvt_pk_bf16_f32 v13, v20, v22
	s_waitcnt lgkmcnt(2)
	v_cvt_pk_bf16_f32 v14, v72, v74
	s_waitcnt lgkmcnt(0)
	v_cvt_pk_bf16_f32 v15, v76, v78
	v_lshl_add_u64 v[82:83], v[80:81], 0, v[0:1]
	global_store_dwordx4 v[82:83], v[12:15], off sc1
	v_or_b32_e32 v0, s8, v59
	v_lshlrev_b32_e32 v0, 11, v0
	v_cvt_pk_bf16_f32 v12, v19, v17
	v_cvt_pk_bf16_f32 v13, v21, v23
	v_cvt_pk_bf16_f32 v14, v73, v75
	v_cvt_pk_bf16_f32 v15, v77, v79
	ds_read2_b32 v[18:19], v63 offset0:49 offset1:57
	ds_read2_b32 v[20:21], v63 offset0:16 offset1:24
	ds_read2_b32 v[22:23], v63 offset0:82 offset1:90
	ds_read2_b32 v[72:73], v63 offset0:115 offset1:123
	ds_read2_b32 v[74:75], v63 offset0:148 offset1:156
	ds_read2_b32 v[76:77], v63 offset0:181 offset1:189
	ds_read2_b32 v[78:79], v63 offset0:214 offset1:222
	ds_read2_b32 v[82:83], v63 offset0:247 offset1:255
	v_lshl_add_u64 v[16:17], v[80:81], 0, v[0:1]
	v_or_b32_e32 v0, s8, v60
	v_lshlrev_b32_e32 v0, 11, v0
	global_store_dwordx4 v[16:17], v[12:15], off sc1
	v_lshl_add_u64 v[16:17], v[80:81], 0, v[0:1]
	v_or_b32_e32 v0, s8, v61
	s_waitcnt lgkmcnt(6)
	v_cvt_pk_bf16_f32 v12, v20, v18
	s_waitcnt lgkmcnt(4)
	v_cvt_pk_bf16_f32 v13, v22, v72
	s_waitcnt lgkmcnt(2)
	v_cvt_pk_bf16_f32 v14, v74, v76
	s_waitcnt lgkmcnt(0)
	v_cvt_pk_bf16_f32 v15, v78, v82
	v_lshlrev_b32_e32 v0, 11, v0
	global_store_dwordx4 v[16:17], v[12:15], off sc1
	v_lshl_add_u64 v[16:17], v[80:81], 0, v[0:1]
	s_nop 0
	v_cvt_pk_bf16_f32 v12, v21, v19
	v_cvt_pk_bf16_f32 v13, v23, v73
	v_cvt_pk_bf16_f32 v14, v75, v77
	v_cvt_pk_bf16_f32 v15, v79, v83
	global_store_dwordx4 v[16:17], v[12:15], off sc1
	s_waitcnt lgkmcnt(0)

; #define LAS __attribute__((address_space(3)))
; __device__ __forceinline__ unsigned pk_bf16(float lo, float hi) { typedef __bf16 b2 __attribute__((ext_vector_type(2))); f32x2 v = {lo, hi}; b2 b = __builtin_convertvector(v, b2); return __builtin_bit_cast(unsigned, b); }
; __device__ __forceinline__ int wt_row_of_col(int n) {
;     if (n < 4096) return n;
;     if (n >= 9216) return 4096 + (n - 9216);
;     int a = n - 4096;
;     if (a < 3072) { const int e = a & 63; a = (a - e) + (e < 32 ? 2 * e : 2 * (e - 32) + 1); }
;     return 6144 + a;
; }
; template <bool MAP> __device__ __forceinline__ void p0_transpose_item(const float* W, int K, int N, u16* WT, LAS float* scr, int item, int lane) {
;     ...
;     const int c = lane & 7;
; #pragma unroll
;     for (int j = 0; j < 4; ++j) { const int n = (lane >> 3) + 8 * j; const LAS float* s = scr + (8 * c) * 33 + n;
;         u32x4 o; o.x = pk_bf16(s[0 * 33], s[1 * 33]); o.y = pk_bf16(s[2 * 33], s[3 * 33]); o.z = pk_bf16(s[4 * 33], s[5 * 33]); o.w = pk_bf16(s[6 * 33], s[7 * 33]);
;         const int r = MAP ? wt_row_of_col(n0 + n) : (n0 + n);
;         *(u32x4*)(WT + (size_t)r * K + k0 + 8 * c) = o; }
.LBB0_40:
	s_or_b64 exec, exec, s[12:13]
	s_ashr_i32 s11, s10, 31
	v_ashrrev_i32_e32 v23, 31, v22
	v_lshl_add_u64 v[12:13], s[10:11], 1, v[4:5]
	s_waitcnt lgkmcnt(3)
	v_cvt_pk_bf16_f32 v72, v14, v15
	v_lshlrev_b64 v[14:15], 11, v[22:23]
	s_waitcnt lgkmcnt(2)
	v_cvt_pk_bf16_f32 v73, v16, v17
	s_waitcnt lgkmcnt(1)
	v_cvt_pk_bf16_f32 v74, v18, v19
	s_waitcnt lgkmcnt(0)
	v_cvt_pk_bf16_f32 v75, v20, v21
	v_lshl_add_u64 v[22:23], v[12:13], 0, v[14:15]
	ds_read2_b32 v[14:15], v63 offset0:8 offset1:41
	ds_read2_b32 v[16:17], v63 offset0:74 offset1:107
	ds_read2_b32 v[18:19], v63 offset0:140 offset1:173
	ds_read2_b32 v[20:21], v63 offset0:206 offset1:239
	global_store_dwordx4 v[22:23], v[72:75], off sc1
	v_add_u32_e32 v23, 8, v0
	v_or_b32_e32 v22, s6, v59
	v_cmp_lt_i32_e32 vcc, s27, v23
	s_and_saveexec_b64 s[10:11], vcc
	s_cbranch_execz .LBB0_45
	s_cmpk_gt_u32 s8, 0x23ff
	s_mov_b64 s[12:13], -1
	s_cbranch_scc1 .LBB0_43
	v_and_b32_e32 v23, 47, v23
	v_lshlrev_b32_e32 v72, 1, v23
	v_add_u32_e32 v22, 0xfffff008, v0
	v_subrev_u32_e32 v73, 63, v72
	v_cmp_gt_u32_e32 vcc, 32, v23
	s_cmpk_lt_u32 s8, 0x1c00
	v_and_b32_e32 v71, 0xffffffc0, v22
	v_cndmask_b32_e32 v23, v73, v72, vcc
	v_add_u32_e32 v23, v23, v71
	s_cselect_b64 vcc, -1, 0
	v_cndmask_b32_e32 v22, v22, v23, vcc
	v_add_u32_e32 v22, 0x1800, v22
	s_mov_b64 s[12:13], 0

; #define LAS __attribute__((address_space(3)))
; __device__ __forceinline__ unsigned pk_bf16(float lo, float hi) { typedef __bf16 b2 __attribute__((ext_vector_type(2))); f32x2 v = {lo, hi}; b2 b = __builtin_convertvector(v, b2); return __builtin_bit_cast(unsigned, b); }
; __device__ __forceinline__ int wt_row_of_col(int n) {
;     if (n < 4096) return n;
;     if (n >= 9216) return 4096 + (n - 9216);
;     int a = n - 4096;
;     if (a < 3072) { const int e = a & 63; a = (a - e) + (e < 32 ? 2 * e : 2 * (e - 32) + 1); }
;     return 6144 + a;
; }
; template <bool MAP> __device__ __forceinline__ void p0_transpose_item(const float* W, int K, int N, u16* WT, LAS float* scr, int item, int lane) {
;     ...
;     const int c = lane & 7;
; #pragma unroll
;     for (int j = 0; j < 4; ++j) { const int n = (lane >> 3) + 8 * j; const LAS float* s = scr + (8 * c) * 33 + n;
;         u32x4 o; o.x = pk_bf16(s[0 * 33], s[1 * 33]); o.y = pk_bf16(s[2 * 33], s[3 * 33]); o.z = pk_bf16(s[4 * 33], s[5 * 33]); o.w = pk_bf16(s[6 * 33], s[7 * 33]);
;         const int r = MAP ? wt_row_of_col(n0 + n) : (n0 + n);
;         *(u32x4*)(WT + (size_t)r * K + k0 + 8 * c) = o; }
.LBB0_45:
	s_or_b64 exec, exec, s[10:11]
	v_ashrrev_i32_e32 v23, 31, v22
	s_waitcnt lgkmcnt(3)
	v_cvt_pk_bf16_f32 v72, v14, v15
	v_lshlrev_b64 v[14:15], 11, v[22:23]
	s_waitcnt lgkmcnt(2)
	v_cvt_pk_bf16_f32 v73, v16, v17
	s_waitcnt lgkmcnt(1)
	v_cvt_pk_bf16_f32 v74, v18, v19
	s_waitcnt lgkmcnt(0)
	v_cvt_pk_bf16_f32 v75, v20, v21
	v_lshl_add_u64 v[22:23], v[12:13], 0, v[14:15]
	ds_read2_b32 v[14:15], v63 offset0:16 offset1:49
	ds_read2_b32 v[16:17], v63 offset0:82 offset1:115
	ds_read2_b32 v[18:19], v63 offset0:148 offset1:181
	ds_read2_b32 v[20:21], v63 offset0:214 offset1:247
	global_store_dwordx4 v[22:23], v[72:75], off sc1
	v_add_u32_e32 v23, 16, v0
	v_or_b32_e32 v22, s6, v60
	v_cmp_lt_i32_e32 vcc, s27, v23
	s_and_saveexec_b64 s[10:11], vcc
	s_cbranch_execz .LBB0_50
	s_cmpk_gt_u32 s8, 0x23ff
	s_mov_b64 s[12:13], -1
	s_cbranch_scc1 .LBB0_48
	v_and_b32_e32 v23, 55, v23
	v_lshlrev_b32_e32 v72, 1, v23
	v_add_u32_e32 v22, 0xfffff010, v0
	v_subrev_u32_e32 v73, 63, v72
	v_cmp_gt_u32_e32 vcc, 32, v23
	s_cmpk_lt_u32 s8, 0x1c00
	v_and_b32_e32 v71, 0xffffffc0, v22
	v_cndmask_b32_e32 v23, v73, v72, vcc
	v_add_u32_e32 v23, v23, v71
	s_cselect_b64 vcc, -1, 0
	v_cndmask_b32_e32 v22, v22, v23, vcc
	v_add_u32_e32 v22, 0x1800, v22
	s_mov_b64 s[12:13], 0

; #define LAS __attribute__((address_space(3)))
; __device__ __forceinline__ unsigned pk_bf16(float lo, float hi) { typedef __bf16 b2 __attribute__((ext_vector_type(2))); f32x2 v = {lo, hi}; b2 b = __builtin_convertvector(v, b2); return __builtin_bit_cast(unsigned, b); }
; __device__ __forceinline__ int wt_row_of_col(int n) {
;     if (n < 4096) return n;
;     if (n >= 9216) return 4096 + (n - 9216);
;     int a = n - 4096;
;     if (a < 3072) { const int e = a & 63; a = (a - e) + (e < 32 ? 2 * e : 2 * (e - 32) + 1); }
;     return 6144 + a;
; }
; template <bool MAP> __device__ __forceinline__ void p0_transpose_item(const float* W, int K, int N, u16* WT, LAS float* scr, int item, int lane) {
;     ...
;     const int c = lane & 7;
; #pragma unroll
;     for (int j = 0; j < 4; ++j) { const int n = (lane >> 3) + 8 * j; const LAS float* s = scr + (8 * c) * 33 + n;
;         u32x4 o; o.x = pk_bf16(s[0 * 33], s[1 * 33]); o.y = pk_bf16(s[2 * 33], s[3 * 33]); o.z = pk_bf16(s[4 * 33], s[5 * 33]); o.w = pk_bf16(s[6 * 33], s[7 * 33]);
;         const int r = MAP ? wt_row_of_col(n0 + n) : (n0 + n);
;         *(u32x4*)(WT + (size_t)r * K + k0 + 8 * c) = o; }
.LBB0_50:
	s_or_b64 exec, exec, s[10:11]
	v_ashrrev_i32_e32 v23, 31, v22
	s_waitcnt lgkmcnt(3)
	v_cvt_pk_bf16_f32 v72, v14, v15
	v_lshlrev_b64 v[14:15], 11, v[22:23]
	s_waitcnt lgkmcnt(2)
	v_cvt_pk_bf16_f32 v73, v16, v17
	s_waitcnt lgkmcnt(1)
	v_cvt_pk_bf16_f32 v74, v18, v19
	s_waitcnt lgkmcnt(0)
	v_cvt_pk_bf16_f32 v75, v20, v21
	v_lshl_add_u64 v[22:23], v[12:13], 0, v[14:15]
	ds_read2_b32 v[14:15], v63 offset0:24 offset1:57
	ds_read2_b32 v[16:17], v63 offset0:90 offset1:123
	ds_read2_b32 v[18:19], v63 offset0:156 offset1:189
	ds_read2_b32 v[20:21], v63 offset0:222 offset1:255
	global_store_dwordx4 v[22:23], v[72:75], off sc1
	v_add_u32_e32 v23, 24, v0
	v_or_b32_e32 v22, s6, v61
	v_cmp_lt_i32_e32 vcc, s27, v23
	s_and_saveexec_b64 s[10:11], vcc
	s_cbranch_execz .LBB0_22
	s_cmpk_gt_u32 s8, 0x23ff
	s_mov_b64 s[12:13], -1
	s_cbranch_scc1 .LBB0_53
	v_and_b32_e32 v23, 63, v23
	v_lshlrev_b32_e32 v72, 1, v23
	v_add_u32_e32 v22, 0xfffff018, v0
	v_subrev_u32_e32 v73, 63, v72
	v_cmp_gt_u32_e32 vcc, 32, v23
	s_cmpk_lt_u32 s8, 0x1c00
	v_and_b32_e32 v71, 0xffffffc0, v22
	v_cndmask_b32_e32 v23, v73, v72, vcc
	v_add_u32_e32 v23, v23, v71
	s_cselect_b64 vcc, -1, 0
	v_cndmask_b32_e32 v22, v22, v23, vcc
	v_add_u32_e32 v22, 0x1800, v22
	s_mov_b64 s[12:13], 0

; __device__ __forceinline__ float wave_sum(float v) {
; #pragma unroll
;     for (int o = 1; o < 64; o <<= 1) v += __shfl_xor(v, o);
;     return v;
; __device__ __forceinline__ void p0_prologue(const Ptrs& P, LAS unsigned char* lds, int vcu, int G) {
;     ...
;     for (int m = gw; m < TT; m += 2 * NGW) {
;         const int m2 = (m + NGW < TT) ? m + NGW : m;
;         const f32x4* xr = (const f32x4*)(P.x + (size_t)m * DM) + lane; const f32x4* xr2 = (const f32x4*)(P.x + (size_t)m2 * DM) + lane; f32x4 v[4], v2[4]; float s = 0.f, s2 = 0.f;
; #pragma unroll
;         for (int j = 0; j < 4; ++j) { v[j] = xr[64 * j]; v2[j] = xr2[64 * j]; }
; #pragma unroll
;         for (int j = 0; j < 4; ++j) { s += (v[j].x * v[j].x + v[j].y * v[j].y) + (v[j].z * v[j].z + v[j].w * v[j].w); s2 += (v2[j].x * v2[j].x + v2[j].y * v2[j].y) + (v2[j].z * v2[j].z + v2[j].w * v2[j].w); }
;         const float rstd = rsqrtf(wave_sum(s) * (1.0f / DM) + NORM_EPS), rstd2 = rsqrtf(wave_sum(s2) * (1.0f / DM) + NORM_EPS);
.LBB0_57:
	s_add_i32 s8, s0, s17
	s_cmpk_lt_i32 s8, 0x4000
	s_cselect_b32 s10, s8, s0
	s_ashr_i32 s1, s0, 31
	s_lshl_b64 s[12:13], s[0:1], 12
	s_ashr_i32 s11, s10, 31
	v_lshl_add_u64 v[22:23], v[2:3], 0, s[12:13]
	global_load_dwordx4 v[14:17], v[4:5], off
	s_lshl_b64 s[12:13], s[10:11], 12
	global_load_dwordx4 v[18:21], v[22:23], off
	global_load_dwordx4 v[26:29], v[22:23], off offset:1024
	global_load_dwordx4 v[30:33], v[22:23], off offset:3072
	global_load_dwordx4 v[34:37], v[22:23], off offset:2048
	v_lshl_add_u64 v[22:23], v[2:3], 0, s[12:13]
	global_load_dwordx4 v[38:41], v[22:23], off
	global_load_dwordx4 v[42:45], v[22:23], off offset:1024
	global_load_dwordx4 v[46:49], v[22:23], off offset:3072
	global_load_dwordx4 v[50:53], v[22:23], off offset:2048
	s_lshl_b64 s[0:1], s[0:1], 11
	v_lshl_add_u64 v[54:55], v[0:1], 0, s[0:1]
	s_lshl_b64 s[0:1], s[10:11], 11
	v_lshl_add_u64 v[56:57], v[0:1], 0, s[0:1]
	s_waitcnt vmcnt(7)
	v_pk_mul_f32 v[22:23], v[20:21], v[20:21]
	v_pk_mul_f32 v[58:59], v[18:19], v[18:19]
	s_waitcnt vmcnt(6)
	v_pk_mul_f32 v[60:61], v[28:29], v[28:29]
	v_pk_mul_f32 v[62:63], v[26:27], v[26:27]
	s_waitcnt vmcnt(4)
	v_mul_f32_e32 v64, v35, v35
	v_mul_f32_e32 v66, v37, v37
	v_pk_mov_b32 v[68:69], v[58:59], v[22:23] op_sel:[1,0]
	v_mov_b32_e32 v59, v23
	s_waitcnt vmcnt(3)
	v_pk_mul_f32 v[22:23], v[40:41], v[40:41]
	v_pk_mul_f32 v[70:71], v[38:39], v[38:39]
	v_pk_mov_b32 v[72:73], v[62:63], v[60:61] op_sel:[1,0]
	v_mov_b32_e32 v63, v61
	s_waitcnt vmcnt(2)
	v_pk_mul_f32 v[60:61], v[44:45], v[44:45]
	v_pk_mul_f32 v[74:75], v[42:43], v[42:43]
	v_mul_f32_e32 v77, v32, v32
	v_mul_f32_e32 v79, v33, v33
	v_pk_fma_f32 v[64:65], v[34:35], v[34:35], v[64:65] op_sel_hi:[1,1,0]
	v_pk_fma_f32 v[66:67], v[36:37], v[36:37], v[66:67] op_sel_hi:[1,1,0]
	v_pk_add_f32 v[58:59], v[68:69], v[58:59]
	v_pk_mov_b32 v[68:69], v[70:71], v[22:23] op_sel:[1,0]
	v_mov_b32_e32 v71, v23
	v_pk_add_f32 v[22:23], v[72:73], v[62:63]
	v_pk_mov_b32 v[62:63], v[74:75], v[60:61] op_sel:[1,0]
	v_mov_b32_e32 v75, v61
	s_waitcnt vmcnt(0)
	v_mul_f32_e32 v76, v51, v51
	v_mul_f32_e32 v78, v53, v53
	v_mov_b32_e32 v65, v77
	v_mov_b32_e32 v67, v79
	v_pk_add_f32 v[68:69], v[68:69], v[70:71]
	v_pk_add_f32 v[62:63], v[62:63], v[74:75]
	v_mul_f32_e32 v13, v30, v30
	v_mul_f32_e32 v25, v31, v31
	v_mul_f32_e32 v80, v46, v46
	v_mul_f32_e32 v81, v47, v47
	v_mul_f32_e32 v82, v48, v48
	v_mul_f32_e32 v83, v49, v49
	v_pk_fma_f32 v[60:61], v[50:51], v[50:51], v[76:77] op_sel_hi:[1,1,0]
	v_pk_fma_f32 v[72:73], v[52:53], v[52:53], v[78:79] op_sel_hi:[1,1,0]
	v_pk_add_f32 v[58:59], v[58:59], v[58:59] op_sel:[0,1] op_sel_hi:[1,0]
	v_pk_add_f32 v[22:23], v[22:23], v[22:23] op_sel:[0,1] op_sel_hi:[1,0]
	v_pk_add_f32 v[64:65], v[64:65], v[66:67]
	v_pk_add_f32 v[66:67], v[68:69], v[68:69] op_sel:[0,1] op_sel_hi:[1,0]
	v_pk_add_f32 v[62:63], v[62:63], v[62:63] op_sel:[0,1] op_sel_hi:[1,0]
	v_mov_b32_e32 v61, v82
	v_mov_b32_e32 v73, v83
	v_mov_b32_e32 v59, v13
	v_mov_b32_e32 v23, v25
	v_mov_b32_e32 v67, v80
	v_mov_b32_e32 v63, v81
	v_pk_add_f32 v[60:61], v[60:61], v[72:73]
	v_pk_add_f32 v[22:23], v[58:59], v[22:23]
	v_pk_add_f32 v[58:59], v[66:67], v[62:63]
	v_pk_add_f32 v[22:23], v[22:23], v[64:65]
	v_pk_add_f32 v[58:59], v[58:59], v[60:61]
	v_mov_b32_e32 v61, v22
	v_mov_b32_e32 v60, v58
	v_mov_b32_e32 v22, v59
	v_pk_add_f32 v[22:23], v[60:61], v[22:23]
	ds_bpermute_b32 v59, v7, v23
	ds_bpermute_b32 v58, v7, v22
	s_waitcnt lgkmcnt(0)
	v_pk_add_f32 v[22:23], v[22:23], v[58:59]
	ds_bpermute_b32 v59, v8, v23
	ds_bpermute_b32 v58, v8, v22
	s_waitcnt lgkmcnt(0)
	v_pk_add_f32 v[22:23], v[22:23], v[58:59]
	ds_bpermute_b32 v59, v9, v23
	ds_bpermute_b32 v58, v9, v22
	s_waitcnt lgkmcnt(0)
	v_pk_add_f32 v[22:23], v[22:23], v[58:59]
	ds_bpermute_b32 v59, v10, v23
	ds_bpermute_b32 v58, v10, v22
	s_waitcnt lgkmcnt(0)
; __device__ __forceinline__ unsigned pk_bf16(float lo, float hi) { typedef __bf16 b2 __attribute__((ext_vector_type(2))); f32x2 v = {lo, hi}; b2 b = __builtin_convertvector(v, b2); return __builtin_bit_cast(unsigned, b); }
; __device__ __forceinline__ void p0_prologue(const Ptrs& P, LAS unsigned char* lds, int vcu, int G) {
;     ...
;         const float rstd = rsqrtf(wave_sum(s) * (1.0f / DM) + NORM_EPS), rstd2 = rsqrtf(wave_sum(s2) * (1.0f / DM) + NORM_EPS);
;         u32x2* o8 = (u32x2*)(H + (size_t)m * DM) + lane; u32x2* o82 = (u32x2*)(H + (size_t)m2 * DM) + lane;
; #pragma unroll
;         for (int j = 0; j < 4; ++j) { const f32x4 w4 = ((const f32x4*)P.norm_w)[lane + 64 * j];
;             o8[64 * j] = (u32x2){pk_bf16(v[j].x * rstd * w4.x, v[j].y * rstd * w4.y), pk_bf16(v[j].z * rstd * w4.z, v[j].w * rstd * w4.w)};
;             o82[64 * j] = (u32x2){pk_bf16(v2[j].x * rstd2 * w4.x, v2[j].y * rstd2 * w4.y), pk_bf16(v2[j].z * rstd2 * w4.z, v2[j].w * rstd2 * w4.w)}; }
;     }
	v_pk_add_f32 v[22:23], v[22:23], v[58:59]
	ds_bpermute_b32 v59, v11, v23
	ds_bpermute_b32 v58, v11, v22
	s_waitcnt lgkmcnt(0)
	v_pk_add_f32 v[22:23], v[22:23], v[58:59]
	ds_bpermute_b32 v59, v12, v23
	ds_bpermute_b32 v58, v12, v22
	s_waitcnt lgkmcnt(0)
	v_pk_add_f32 v[22:23], v[22:23], v[58:59]
	s_nop 0
	v_pk_fma_f32 v[22:23], v[22:23], s[6:7], v[6:7] op_sel_hi:[1,0,0]
	s_nop 0
	v_mul_f32_e32 v13, 0x4b800000, v23
	v_cmp_gt_f32_e64 s[0:1], s7, v23
	v_mul_f32_e32 v25, 0x4b800000, v22
	v_cmp_gt_f32_e32 vcc, s7, v22
	v_cndmask_b32_e64 v13, v23, v13, s[0:1]
	v_rsq_f32_e32 v13, v13
	v_cndmask_b32_e32 v22, v22, v25, vcc
	v_rsq_f32_e32 v23, v22
	v_mul_f32_e32 v22, 0x45800000, v13
	v_cndmask_b32_e64 v22, v13, v22, s[0:1]
	v_mul_f32_e32 v25, 0x45800000, v23
	v_cndmask_b32_e32 v58, v23, v25, vcc
	v_pk_mul_f32 v[18:19], v[18:19], v[22:23] op_sel_hi:[1,0]
	v_pk_mul_f32 v[20:21], v[20:21], v[22:23] op_sel_hi:[1,0]
	v_pk_mul_f32 v[38:39], v[38:39], v[58:59] op_sel_hi:[1,0]
	v_pk_mul_f32 v[40:41], v[40:41], v[58:59] op_sel_hi:[1,0]
	v_pk_mul_f32 v[18:19], v[14:15], v[18:19]
	v_pk_mul_f32 v[20:21], v[16:17], v[20:21]
	v_pk_mul_f32 v[14:15], v[14:15], v[38:39]
	v_pk_mul_f32 v[16:17], v[16:17], v[40:41]
	v_cvt_pk_bf16_f32 v18, v18, v19
	v_cvt_pk_bf16_f32 v19, v20, v21
	v_cvt_pk_bf16_f32 v14, v14, v15
	v_cvt_pk_bf16_f32 v15, v16, v17
	global_store_dwordx2 v[54:55], v[18:19], off sc1
	global_store_dwordx2 v[56:57], v[14:15], off sc1
	global_load_dwordx4 v[14:17], v[4:5], off offset:1024
	v_pk_mul_f32 v[18:19], v[26:27], v[22:23] op_sel_hi:[1,0]
	v_pk_mul_f32 v[20:21], v[28:29], v[22:23] op_sel_hi:[1,0]
	v_pk_mul_f32 v[26:27], v[42:43], v[58:59] op_sel_hi:[1,0]
	v_pk_mul_f32 v[28:29], v[44:45], v[58:59] op_sel_hi:[1,0]
	s_add_i32 s0, s8, s17
	s_cmpk_gt_i32 s0, 0x3fff
	s_waitcnt vmcnt(0)
	v_pk_mul_f32 v[18:19], v[14:15], v[18:19]
	v_pk_mul_f32 v[20:21], v[16:17], v[20:21]
	v_pk_mul_f32 v[14:15], v[14:15], v[26:27]
	v_pk_mul_f32 v[16:17], v[16:17], v[28:29]
	v_cvt_pk_bf16_f32 v18, v18, v19
	v_cvt_pk_bf16_f32 v19, v20, v21
	v_cvt_pk_bf16_f32 v14, v14, v15
	v_cvt_pk_bf16_f32 v15, v16, v17
	global_store_dwordx2 v[54:55], v[18:19], off offset:512 sc1
	global_store_dwordx2 v[56:57], v[14:15], off offset:512 sc1
	global_load_dwordx4 v[14:17], v[4:5], off offset:2048
	v_pk_mul_f32 v[18:19], v[34:35], v[22:23] op_sel_hi:[1,0]
	v_pk_mul_f32 v[20:21], v[36:37], v[22:23] op_sel_hi:[1,0]
	v_pk_mul_f32 v[26:27], v[50:51], v[58:59] op_sel_hi:[1,0]
	v_pk_mul_f32 v[28:29], v[52:53], v[58:59] op_sel_hi:[1,0]
	s_waitcnt vmcnt(0)
	v_pk_mul_f32 v[18:19], v[18:19], v[14:15]
	v_pk_mul_f32 v[20:21], v[20:21], v[16:17]
	v_pk_mul_f32 v[14:15], v[14:15], v[26:27]
	v_pk_mul_f32 v[16:17], v[16:17], v[28:29]
	v_cvt_pk_bf16_f32 v18, v18, v19
	v_cvt_pk_bf16_f32 v19, v20, v21
	v_cvt_pk_bf16_f32 v14, v14, v15
	v_cvt_pk_bf16_f32 v15, v16, v17
	global_store_dwordx2 v[54:55], v[18:19], off offset:1024 sc1
	global_store_dwordx2 v[56:57], v[14:15], off offset:1024 sc1
	global_load_dwordx4 v[14:17], v[4:5], off offset:3072
	v_pk_mul_f32 v[18:19], v[30:31], v[22:23] op_sel_hi:[1,0]
	v_pk_mul_f32 v[20:21], v[32:33], v[22:23] op_sel_hi:[1,0]
	v_pk_mul_f32 v[22:23], v[46:47], v[58:59] op_sel_hi:[1,0]
	v_pk_mul_f32 v[26:27], v[48:49], v[58:59] op_sel_hi:[1,0]
	s_waitcnt vmcnt(0)
	v_pk_mul_f32 v[18:19], v[18:19], v[14:15]
	v_pk_mul_f32 v[20:21], v[20:21], v[16:17]
	v_pk_mul_f32 v[14:15], v[22:23], v[14:15]
	v_pk_mul_f32 v[16:17], v[26:27], v[16:17]
	v_cvt_pk_bf16_f32 v18, v18, v19
	v_cvt_pk_bf16_f32 v19, v20, v21
	v_cvt_pk_bf16_f32 v14, v14, v15
	v_cvt_pk_bf16_f32 v15, v16, v17
	global_store_dwordx2 v[54:55], v[18:19], off offset:1536 sc1
	global_store_dwordx2 v[56:57], v[14:15], off offset:1536 sc1
	s_cbranch_scc0 .LBB0_57

; __device__ __forceinline__ void p0_prologue(const Ptrs& P, LAS unsigned char* lds, int vcu, int G) {
;     ...
;     float* cosT = (float*)(P.ws + WS_COS); float* sinT = (float*)(P.ws + WS_SIN);
;     for (int e = (vcu * 512 + tid); e < TT * 32; e += G * 512) {
;         const int row = e >> 5, j = e & 31;
;         const float inv = exp2f(-(float)j * (13.287712379549449f / 32.0f));
;         const float ang = (float)P.pos[row] * inv;
;         const double rev = (double)ang * 0.15915494309189535; const float fr = (float)(rev - __builtin_rint(rev));
;         cosT[e] = __builtin_amdgcn_cosf(fr); sinT[e] = __builtin_amdgcn_sinf(fr);
;     }
.LBB0_60:
	v_ashrrev_i32_e32 v6, 5, v0
	v_ashrrev_i32_e32 v7, 31, v6
	s_waitcnt lgkmcnt(0)
	v_lshl_add_u64 v[6:7], v[6:7], 2, s[58:59]
	global_load_dword v1, v[6:7], off
	v_add_co_u32_e32 v6, vcc, 0x200000, v2
	v_add_u32_e32 v0, s6, v0
	s_nop 0
	v_addc_co_u32_e32 v7, vcc, 0, v3, vcc
	v_cmp_lt_i32_e32 vcc, s7, v0
	s_or_b64 s[10:11], vcc, s[10:11]
	s_waitcnt vmcnt(0)
	v_cvt_f32_i32_e32 v1, v1
	v_mul_f32_e32 v1, v4, v1
	v_cvt_f64_f32_e32 v[8:9], v1
	v_mul_f64 v[10:11], v[8:9], s[12:13]
	v_rndne_f64_e32 v[10:11], v[10:11]
	v_fma_f64 v[8:9], v[8:9], s[12:13], -v[10:11]
	v_cvt_f32_f64_e32 v1, v[8:9]
	v_cos_f32_e32 v5, v1
	v_sin_f32_e32 v1, v1
	global_store_dword v[2:3], v5, off sc1
	global_store_dword v[6:7], v1, off sc1
	v_lshl_add_u64 v[2:3], v[2:3], 0, s[8:9]
	s_andn2_b64 exec, exec, s[10:11]
	s_cbranch_execnz .LBB0_60
